# static priority raise (s_setprio 1) for waves 4-7 during the HGRN scan and the MLA tile loops
# speedup vs baseline: 1.0005x; 1.0005x over previous
; template <bool DRY> __device__ __forceinline__ void hgrn_unit(LAS unsigned char* lds, int b, int h, int vs, int layer, bf16_t* Pm, const float* lbraw) {
;     ...
;     __syncthreads();
; __global__ void __launch_bounds__(NTHREADS, 2) fwd_megakernel(Params Pkern) {
;     ...
;             if (PM(12)) { SETUP const float* lbraw = Pp->lbraw; if (DUPMASK & 1) for (int u = blockIdx.x; u < 256; u += gridDim.x) hgrn_unit<true>(lds, u >> 4, (u >> 2) & 3, u & 3, layer, PB, lbraw);
;               for (int u = blockIdx.x; u < 256; u += gridDim.x) hgrn_unit<false>(lds, u >> 4, (u >> 2) & 3, u & 3, layer, PB, lbraw); }
.LBB0_611:
	s_setprio 0
	s_add_i32 s22, s22, s20
	s_cmpk_gt_i32 s22, 0xff
	s_waitcnt vmcnt(0)
	s_barrier
	s_cbranch_scc1 .LBB0_647

; #define LAS __attribute__((address_space(3)))
; __device__ __forceinline__ int otid() { int t = threadIdx.x; asm volatile("" : "+v"(t)); return t; }
; template <bool DRY> __device__ __forceinline__ void hgrn_unit(LAS unsigned char* lds, int b, int h, int vs, int layer, bf16_t* Pm, const float* lbraw) {
;     using namespace hg;
;     const int tid = otid(), lane = tid & 63; const int wid = __builtin_amdgcn_readfirstlane(tid >> 6);
;     const size_t tok0 = (size_t)b * SEQ;
;     const int kl = lane & 15, tq = lane >> 4, kch = 16 * wid + kl;
;     (void)layer; (void)lbraw;
;     const bf16_t* qsrc = Pm + (tok0 + 4 * tq) * PW + PC_HQ + h * 128 + (kch & ~1);
;     const bf16_t* fsrc = Pm + (tok0 + 4 * tq) * PW + PC_HF + h * 128 + (kch & ~1);
;     const bool isv = tid < 128; const int vv = tid & 31, vtq = (tid >> 5) & 3;
;     const bf16_t* vsrc = Pm + (tok0 + 4 * vtq) * PW + PC_HI + h * 128 + vs * 32 + (vv & ~1);
;     constexpr int NSTEP = SEQ / 16;
;     for (int i = tid; i < SB / 4; i += NTHREADS) ((LAS unsigned*)(lds + OFF_S + SB))[i] = 0u;
;     Raw ra, rb;
;     load_raw(ra, qsrc, fsrc, vsrc, 0, isv);
;     prep(ra, lds, lane, kch, tq, isv, vv, vtq);
;     load_raw(ra, qsrc, fsrc, vsrc, 1, isv); load_raw(rb, qsrc, fsrc, vsrc, 2, isv);
;     f32x16 sacc = {};
;     const int c16 = lane & 15, kq = lane >> 4, r32 = lane & 31, hh = lane >> 5;
;     __syncthreads();
.LBB0_615:
	s_or_b64 exec, exec, s[6:7]
	s_ashr_i32 s6, s22, 4
	s_ashr_i32 s7, s6, 31
	v_bfe_u32 v9, v3, 4, 2
	s_lshl_b64 s[14:15], s[6:7], 11
	v_lshlrev_b32_e32 v8, 2, v9
	v_or_b32_e32 v0, s14, v8
	v_mov_b64_e32 v[4:5], s[4:5]
	v_bfe_u32 v12, v3, 5, 2
	s_ashr_i32 s28, s10, 6
	s_mov_b32 s65, s28
	s_cmp_ge_u32 s65, 4
	s_cbranch_scc0 .Lprio_hg
	s_setprio 1
.Lprio_hg:
	v_mad_u64_u32 v[0:1], s[6:7], v0, s24, v[4:5]
	s_lshl_b32 s10, s22, 5
	v_lshl_or_b32 v6, v12, 2, s14
	s_and_b32 s6, s10, 0x180
	v_mad_u64_u32 v[4:5], s[8:9], v6, s24, v[4:5]
	v_and_b32_e32 v7, 15, v3
	s_lshl_b32 s34, s28, 4
	v_mad_i32_i24 v1, s15, v240, v1
	s_lshl_b32 s6, s6, 1
	s_mov_b32 s7, s29
	v_mad_i32_i24 v5, s15, v240, v5
	v_lshl_add_u64 v[0:1], v[0:1], 0, s[6:7]
	v_bitop3_b32 v10, s34, -2, v7 bitop3:0xc8
	v_lshl_add_u64 v[4:5], v[4:5], 0, s[6:7]
	s_and_b32 s7, s10, 0x60
	v_ashrrev_i32_e32 v11, 31, v10
	s_lshl_b32 s8, s7, 1
	s_mul_i32 s41, s14, 0x1d40
	s_add_u32 s38, s4, s41
	s_addc_u32 s39, s5, 0
	s_add_u32 s38, s38, s6
	s_addc_u32 s39, s39, 0
	s_add_u32 s38, s38, 0xd00
	s_addc_u32 s39, s39, 0
	s_mov_b32 s9, s29
	v_and_b32_e32 v6, 30, v3
	v_lshl_add_u64 v[0:1], v[10:11], 1, v[0:1]
	v_lshl_add_u64 v[4:5], v[4:5], 0, s[8:9]
	v_lshlrev_b32_e32 v10, 1, v6
	v_mov_b32_e32 v11, v2
	s_movk_i32 s7, 0x1000
	v_lshl_add_u64 v[4:5], v[4:5], 0, v[10:11]
	v_add_co_u32_e32 v10, vcc, s7, v0
	v_cmp_eq_u32_e64 s[50:51], 3, v9
	s_nop 0
	v_addc_co_u32_e32 v11, vcc, 0, v1, vcc
	v_add_co_u32_e32 v14, vcc, s7, v4
	s_movk_i32 s7, 0x2000
	s_nop 0
	v_addc_co_u32_e32 v15, vcc, 0, v5, vcc
	v_add_co_u32_e32 v16, vcc, s7, v0
	s_movk_i32 s7, 0x3000
	s_nop 0
	v_addc_co_u32_e32 v17, vcc, 0, v1, vcc
	v_add_co_u32_e32 v18, vcc, s7, v4
	s_movk_i32 s7, 0x4000
	s_nop 0
	v_addc_co_u32_e32 v19, vcc, 0, v5, vcc
	v_add_co_u32_e32 v20, vcc, s7, v0
	s_nop 1
	v_addc_co_u32_e32 v21, vcc, 0, v1, vcc
	s_nop 0
	s_nop 0
	s_nop 0
	s_nop 0
	v_add_co_u32_e32 v10, vcc, s7, v4
	s_movk_i32 s7, 0x6000
	s_nop 0
	v_addc_co_u32_e32 v11, vcc, 0, v5, vcc
	v_add_co_u32_e32 v10, vcc, s7, v0
	s_nop 1
	v_addc_co_u32_e32 v11, vcc, 0, v1, vcc
	v_add_co_u32_e32 v18, vcc, s7, v4
	s_movk_i32 s7, 0x440
	s_nop 0
	v_addc_co_u32_e32 v19, vcc, 0, v5, vcc
	s_nop 0
	v_and_b32_e32 v19, 1, v3
	v_cmp_eq_u32_e64 s[44:45], 0, v19
	v_and_b32_e32 v11, 63, v3
	v_cmp_gt_u32_e64 s[46:47], 16, v11
	v_cmp_lt_u32_e64 s[48:49], 31, v11
	v_or_b32_e32 v10, s34, v7
	v_lshl_add_u32 v36, v10, 1, 0
	v_mad_u32_u24 v42, v9, s7, v36
	v_bfe_u32 v140, v234, 4, 2
	v_mul_u32_u24_e32 v136, 0x440, v140
	v_lshrrev_b32_e32 v140, 6, v234
	v_and_b32_e32 v141, 15, v234
	v_lshl_or_b32 v140, v140, 4, v141
	v_lshrrev_b32_e32 v140, 1, v140
	v_lshl_add_u32 v136, v140, 2, v136
	v_add_u32_e32 v136, 0xd400, v136
	v_bfe_i32 v145, v234, 4, 1
	v_and_b32_e32 v151, 1, v234
	v_mov_b32_e32 v152, 0x2020000
	v_mul_lo_u32 v151, v151, v152
	v_add_u32_e32 v151, 0x1000c0c, v151
	v_and_b32_e32 v186, 1, v234
	v_mov_b32_e32 v187, 0x403fbfc
	v_mul_lo_u32 v154, v186, v187
	v_add_u32_e32 v154, 0x1000504, v154
	v_add_u32_e32 v155, 0x2020202, v154
	v_mul_u32_u24_e32 v187, 0x220, v186
	v_add_u32_e32 v186, 0x3800, v187
	v_and_b32_e32 v144, 1, v234
	v_lshl_add_u32 v144, v144, 1, v136
	v_bfe_u32 v140, v234, 5, 2
	v_and_b32_e32 v141, 31, v234
	v_lshrrev_b32_e32 v141, 1, v141
	v_lshlrev_b32_e32 v141, 2, v141
	v_lshl_add_u32 v137, v140, 8, v141
	v_add_u32_e32 v137, 0xf600, v137
	v_and_b32_e32 v140, 63, v234
	v_lshrrev_b32_e32 v141, 4, v140
	v_lshrrev_b32_e32 v142, 6, v234
	v_and_b32_e32 v143, 3, v142
	v_lshl_add_u32 v141, v143, 2, v141
	v_mul_u32_u24_e32 v138, 0x1d40, v141
	v_and_b32_e32 v141, 15, v140
	v_lshl_add_u32 v138, v141, 4, v138
	v_lshrrev_b32_e32 v142, 2, v142
	v_lshl_add_u32 v138, v142, 10, v138
	v_lshrrev_b32_e32 v141, 2, v140
	v_mul_u32_u24_e32 v139, 0x1d40, v141
	v_and_b32_e32 v141, 3, v140
	v_lshl_add_u32 v139, v141, 4, v139
	v_add_u32_e32 v139, 0x800, v139
	v_add_u32_e32 v139, s8, v139
	s_mul_i32 s64, s65, 0x440
	s_add_i32 s64, s64, 0xd400
	s_mov_b64 s[42:43], s[38:39]
	s_cmp_lg_u32 s65, 7
	s_cbranch_scc1 .Lhg_pro_nov
	s_add_i32 m0, s64, 0
	s_nop 0
	global_load_lds_dwordx4 v138, s[42:43]
	s_mov_b32 m0, 0xf600
	s_nop 0
	global_load_lds_dwordx4 v139, s[42:43]
	s_add_u32 s42, s42, 0x1d400
	s_addc_u32 s43, s43, 0
	s_add_i32 m0, s64, 9792
	s_nop 0
	global_load_lds_dwordx4 v138, s[42:43]
	s_mov_b32 m0, 0x11c40
	s_nop 0
	global_load_lds_dwordx4 v139, s[42:43]
	s_add_u32 s42, s42, 0x1d400
	s_addc_u32 s43, s43, 0
	s_add_i32 m0, s64, 19584
	s_nop 0
	global_load_lds_dwordx4 v138, s[42:43]
	s_mov_b32 m0, 0x14280
	s_nop 0
	global_load_lds_dwordx4 v139, s[42:43]
	s_add_u32 s42, s42, 0x1d400
	s_addc_u32 s43, s43, 0
	s_add_i32 m0, s64, 29376
	s_nop 0
	global_load_lds_dwordx4 v138, s[42:43]
	s_mov_b32 m0, 0x168c0
	s_nop 0
	global_load_lds_dwordx4 v139, s[42:43]
	s_waitcnt vmcnt(4)
	s_branch .Lhg_pro_done

; #define LAS __attribute__((address_space(3)))
; __device__ __forceinline__ int otid() { int t = threadIdx.x; asm volatile("" : "+v"(t)); return t; }
; template <bool DRY> __device__ __forceinline__ void mla_unit(LAS unsigned char* lds, int b, int h, int qb, const bf16_t* Q, const bf16_t* Kn, const bf16_t* Pm, const bf16_t* VT, bf16_t* Y) {
;     const int tid = otid(), lane = tid & 63, r32 = lane & 31, hi = lane >> 5; const int wid = __builtin_amdgcn_readfirstlane(tid >> 6);
;     const int NT = 4 * qb + 4, tmax = 4 * qb + (wid >> 1);
;     const size_t tok0 = (size_t)b * SEQ;
;     const size_t qtok = tok0 + qb * 256 + wid * 32 + r32;
;     const bf16_t* qrow = Q + qtok * 768;
;     bf16x8 qf[6];
; #pragma unroll
;     for (int s = 0; s < 4; ++s) qf[s] = *(const bf16x8*)(qrow + h * 64 + 16 * s + 8 * hi);
; #pragma unroll
;     for (int s = 0; s < 2; ++s) qf[4 + s] = *(const bf16x8*)(qrow + 512 + h * 32 + 16 * s + 8 * hi);
;     const int ka_row = tid >> 3, ka_c = tid & 7, kb_row = (tid & 255) >> 2, kb_c = tid & 3;
;     const bf16_t* ka_src = Kn + (tok0 + ka_row) * 512 + h * 64 + ka_c * 8;
;     const bf16_t* kb_src = Pm + (tok0 + kb_row) * PW + PC_KR + kb_c * 8;
;     const bf16_t* va_src = VT + (size_t)(h * 64 + ka_row) * VTLD + tok0 + ka_c * 8;
;     const int ka_dst = ka_row * MLA_KSTR + ka_c * 16, kb_dst = kb_row * MLA_KSTR + 128 + kb_c * 16, va_dst = ka_row * MLA_VSTR + ka_c * 16;
;     u32x4 ra = *(const u32x4*)ka_src, rb = *(const u32x4*)kb_src, rv = *(const u32x4*)va_src;
;     float m_run = -1e30f, l_run = 0.f; f32x16 o0 = {}, o1 = {};
;     const float C = 0.10206207261596577f * 1.4426950408889634f;
;     for (int t = 0; t < NT; ++t) {
;         LAS unsigned char* kbuf = lds + (t & 1) * MLA_KB; LAS unsigned char* vbuf = lds + 2 * MLA_KB + (t & 1) * MLA_VB;
;         *(LAS u32x4*)(kbuf + ka_dst) = ra; if (tid < 256) *(LAS u32x4*)(kbuf + kb_dst) = rb; *(LAS u32x4*)(vbuf + va_dst) = rv;
.LBB0_801:
	s_lshr_b32 s22, s55, 1
	s_or_b32 s22, s22, s53
	s_and_b32 s23, s55, 1
	s_sub_i32 s28, 7, s22
	v_mov_b32_e32 v3, v234
	s_cmp_eq_u32 s23, 0
	s_cselect_b32 s42, s22, s28
	v_readfirstlane_b32 s43, v3
	v_and_b32_e32 v14, 31, v3
	s_bitcmp1_b32 s43, 8
	s_cbranch_scc0 .Lprio_ml
	s_setprio 1
.Lprio_ml:
	s_ashr_i32 s22, s43, 1
	s_andn2_b32 s22, s22, 31
	v_lshl_or_b32 v0, s42, 8, v14
	s_ashr_i32 s23, s22, 31
	v_or_b32_e32 v0, s10, v0
	v_mov_b32_e32 v1, s11
	v_lshl_add_u64 v[0:1], v[0:1], 0, s[22:23]
	v_mov_b64_e32 v[4:5], s[8:9]
	v_bfe_u32 v16, v3, 2, 6
	v_mad_u64_u32 v[4:5], s[22:23], v0, s21, v[4:5]
	v_ashrrev_i32_e32 v6, 3, v3
	v_lshlrev_b32_e32 v12, 4, v3
	v_or_b32_e32 v13, s10, v16
	v_mov_b64_e32 v[10:11], s[6:7]
	v_bfe_u32 v15, v3, 5, 1
	v_mad_i32_i24 v5, v1, s21, v5
	s_lshl_b32 s28, s54, 1
	v_and_b32_e32 v110, 0x70, v12
	v_mad_u64_u32 v[10:11], s[22:23], v13, s24, v[10:11]
	v_and_b32_e32 v112, 48, v12
	v_add_u32_e32 v17, s54, v6
	v_mov_b64_e32 v[12:13], s[14:15]
	v_lshl_add_u64 v[104:105], v[4:5], 0, s[28:29]
	v_lshlrev_b32_e32 v108, 4, v15
	v_mov_b32_e32 v109, v2
	s_mov_b32 s41, s29
	v_ashrrev_i32_e32 v7, 31, v6
	v_mad_i32_i24 v11, s11, v240, v11
	v_mov_b32_e32 v113, v2
	v_mad_i64_i32 v[12:13], s[22:23], v17, s37, v[12:13]
	v_lshl_add_u64 v[0:1], v[104:105], 0, v[108:109]
	v_lshl_add_u64 v[4:5], v[4:5], 0, s[40:41]
	v_lshl_add_u64 v[8:9], s[10:11], 0, v[6:7]
	v_mov_b32_e32 v111, v2
	v_lshl_add_u64 v[10:11], v[10:11], 0, v[112:113]
	s_mov_b32 s22, 0x8101000
	global_load_dwordx4 v[68:71], v[0:1], off offset:32
	global_load_dwordx4 v[72:75], v[0:1], off offset:64
	v_lshl_add_u64 v[4:5], v[4:5], 0, v[108:109]
	global_load_dwordx4 v[76:79], v[0:1], off offset:96
	global_load_dwordx4 v[80:83], v[4:5], off offset:1024
	v_lshlrev_b64 v[8:9], 10, v[8:9]
	v_lshl_add_u64 v[114:115], v[12:13], 0, v[110:111]
	global_load_dwordx4 v[84:87], v[0:1], off
	global_load_dwordx4 v[88:91], v[114:115], off
	v_add_co_u32_e32 v0, vcc, s22, v10
	v_lshl_add_u64 v[8:9], s[12:13], 0, v[8:9]
	s_nop 0
	v_addc_co_u32_e32 v1, vcc, 0, v11, vcc
	v_lshl_add_u64 v[8:9], v[8:9], 0, v[110:111]
	global_load_dwordx4 v[96:99], v[0:1], off offset:3328
	global_load_dwordx4 v[92:95], v[4:5], off offset:1056
	global_load_dwordx4 v[100:103], v[8:9], off
	s_lshl_b32 s22, s42, 2
	s_ashr_i32 s56, s43, 7
	v_mul_u32_u24_e32 v0, 0x1d40, v16
	s_add_i32 s41, s22, 4
	s_add_i32 s56, s56, s22
	s_movk_i32 s22, 0xd0
	v_mul_hi_u32_u24_e32 v1, 0x1d40, v16
	v_or_b32_e32 v0, v0, v112
	v_mul_lo_u32 v107, v6, s22
	s_movk_i32 s22, 0x90
	v_lshl_add_u64 v[116:117], s[34:35], 0, v[0:1]
	v_lshlrev_b64 v[0:1], 10, v[6:7]
	v_lshlrev_b32_e32 v106, 3, v15
	v_mul_lo_u32 v111, v6, s22
	s_movk_i32 s22, 0x100
	v_mul_u32_u24_e32 v113, 0xd0, v14
	v_mul_u32_u24_e32 v120, 0x90, v14
	v_or_b32_e32 v0, v0, v110
	v_mov_b32_e32 v14, v2
	v_mov_b32_e32 v15, v2
	v_cmp_gt_i32_e64 s[42:43], s22, v3
	v_lshl_add_u64 v[118:119], s[38:39], 0, v[0:1]
	v_mov_b32_e32 v0, v2
	v_mov_b32_e32 v1, v2
	v_mov_b32_e32 v3, v2
	v_mov_b32_e32 v4, v2
	v_mov_b32_e32 v5, v2
	v_mov_b32_e32 v6, v2
	v_mov_b32_e32 v7, v2
	v_mov_b32_e32 v8, v2
	v_mov_b32_e32 v9, v2
	v_mov_b32_e32 v10, v2
	v_mov_b32_e32 v11, v2
	v_mov_b32_e32 v12, v2
	v_mov_b32_e32 v13, v2
	v_mov_b64_e32 v[34:35], v[14:15]
	v_mul_u32_u24_e32 v109, 0xd0, v16
	v_mov_b64_e32 v[32:33], v[12:13]
	v_mov_b64_e32 v[30:31], v[10:11]
	v_mov_b64_e32 v[28:29], v[8:9]
	v_mov_b64_e32 v[26:27], v[6:7]
	v_mov_b64_e32 v[24:25], v[4:5]
	v_mov_b64_e32 v[22:23], v[2:3]
	v_mov_b64_e32 v[20:21], v[0:1]
	v_mov_b64_e32 v[18:19], v[14:15]
	v_mov_b32_e32 v122, 0xf149f2ca
	v_mov_b32_e32 v121, 0
	s_mov_b32 s28, 64
	v_mov_b64_e32 v[16:17], v[12:13]
	v_mov_b64_e32 v[14:15], v[10:11]
	v_mov_b64_e32 v[12:13], v[8:9]
	v_mov_b64_e32 v[10:11], v[6:7]
	v_mov_b64_e32 v[8:9], v[4:5]
	v_mov_b64_e32 v[6:7], v[2:3]
	v_mov_b64_e32 v[4:5], v[0:1]
	s_mov_b32 s57, 0
	s_and_b32 s59, s57, 1
	s_mul_i32 s22, s59, 0x3400
	s_add_i32 s58, s22, 0
	v_add3_u32 v0, s58, v107, v110
	s_waitcnt vmcnt(0)
	ds_write_b128 v0, v[100:103]
	s_and_saveexec_b64 s[22:23], s[42:43]
	v_add3_u32 v0, s58, v109, v112
	ds_write_b128 v0, v[96:99] offset:128
	s_or_b64 exec, exec, s[22:23]
	s_lshl_b32 s22, s59, 12
	s_sub_i32 s23, s58, s22
	v_add3_u32 v0, s23, v111, v110
	ds_write_b128 v0, v[88:91] offset:26624

; __device__ __forceinline__ int otid() { int t = threadIdx.x; asm volatile("" : "+v"(t)); return t; }
; __device__ __forceinline__ void unpack8(u32x4 w, f32x4& a, f32x4& b) { a = (f32x4){bflo(w.x), bfhi(w.x), bflo(w.y), bfhi(w.y)}; b = (f32x4){bflo(w.z), bfhi(w.z), bflo(w.w), bfhi(w.w)}; }
; __device__ __forceinline__ void hgrn_finish(bf16_t* Pm, const float* normw) {
;     const int tid = otid(); const int lane = tid & 63, wid = tid >> 6;
;     const int gw = blockIdx.x * NWAVES + wid, NGW = gridDim.x * NWAVES;
;     f32x4 w0 = *(const f32x4*)(normw + lane * 8), w1 = *(const f32x4*)(normw + lane * 8 + 4);
;     for (int t = gw; t < T; t += NGW) {
;         bf16_t* op = Pm + (size_t)t * PW + PC_HI + lane * 8; const bf16_t* gp = Pm + (size_t)t * PW + PC_HG + lane * 8;
;         f32x4 a, b, g0, g1; unpack8(*(const u32x4*)op, a, b); unpack8(*(const u32x4*)gp, g0, g1);
.LBB0_813:
	s_setprio 0
	s_mov_b64 s[8:9], s[90:91]
	v_mov_b32_e32 v0, v234
	s_mov_b32 s6, 0x8000
	v_mov_b32_e32 v0, v234
	s_nop 0
	v_ashrrev_i32_e32 v1, 6, v0
	v_add_u32_e32 v3, s93, v1
	v_cmp_gt_i32_e32 vcc, s6, v3
	s_and_saveexec_b64 s[6:7], vcc
	s_cbranch_execz .LBB0_816
	s_waitcnt lgkmcnt(0)
	s_load_dwordx2 s[10:11], s[8:9], 0x68
	v_readlane_b32 s12, v252, 11
	v_readlane_b32 s13, v252, 12
	s_lshl_b32 s28, s12, 9
	s_lshl_b64 s[12:13], s[28:29], 2
	v_lshlrev_b32_e32 v1, 5, v0
	s_waitcnt lgkmcnt(0)
	s_add_u32 s10, s10, s12
	v_and_b32_e32 v1, 0x7e0, v1
	s_addc_u32 s11, s11, s13
	global_load_dwordx4 v[4:7], v1, s[10:11]
	global_load_dwordx4 v[8:11], v1, s[10:11] offset:16
	v_xor_b32_e32 v1, 1, v238
	v_add_u32_e32 v15, 64, v239
	v_cmp_lt_i32_e32 vcc, v1, v15
	s_load_dwordx2 s[8:9], s[8:9], 0xd0
	v_and_b32_e32 v0, 63, v0
	v_cndmask_b32_e32 v1, v238, v1, vcc
	v_lshlrev_b32_e32 v12, 2, v1
	v_xor_b32_e32 v1, 2, v238
	v_cmp_lt_i32_e32 vcc, v1, v15
	v_lshlrev_b32_e32 v0, 4, v0
	s_nop 0
	v_cndmask_b32_e32 v1, v238, v1, vcc
	v_lshlrev_b32_e32 v13, 2, v1
	v_xor_b32_e32 v1, 4, v238
	v_cmp_lt_i32_e32 vcc, v1, v15
	s_nop 1
	v_cndmask_b32_e32 v1, v238, v1, vcc
	v_lshlrev_b32_e32 v14, 2, v1
	v_xor_b32_e32 v1, 8, v238
	v_cmp_lt_i32_e32 vcc, v1, v15
	s_nop 1
	v_cndmask_b32_e32 v1, v238, v1, vcc
	v_lshlrev_b32_e32 v15, 2, v1
	v_mov_b32_e32 v1, v2
	v_mad_i64_i32 v[0:1], s[10:11], v3, s24, v[0:1]
	s_waitcnt lgkmcnt(0)
	v_lshl_add_u64 v[0:1], s[8:9], 0, v[0:1]
	s_mov_b64 s[8:9], 0x8101500
	v_lshl_add_u64 v[0:1], v[0:1], 0, s[8:9]
	s_mov_b64 s[8:9], 0
	global_load_dwordx4 v[16:19], v[0:1], off
	global_load_dwordx4 v[20:23], v[0:1], off offset:1024
	s_waitcnt vmcnt(0)
